# attention QK block: K-fragment LDS reads double-buffered one k-step ahead in free VGPRs, first reads hoisted to step head, exp/cvt reordered to drop s_nops
# speedup vs baseline: 1.0183x; 1.0085x over previous
; #define SBAR() __builtin_amdgcn_sched_barrier(0)
; __device__ __forceinline__ void attn_qk(const unsigned char* Kb, const bf16x8 (&qr)[6], const f32x16& negm, f32x16& s0, f32x16& s1, int r32, int hi) {
;     constexpr int KROW = 208;
; #pragma unroll
;     for (int d0 = 0; d0 < 6; ++d0) {
;         const bf16x8 a0 = *(const bf16x8*)(Kb + r32 * KROW + d0 * 32 + hi * 16);
;         const bf16x8 a1 = *(const bf16x8*)(Kb + (32 + r32) * KROW + d0 * 32 + hi * 16);
;         s0 = __builtin_amdgcn_mfma_f32_32x32x16_bf16(a0, qr[d0], d0 == 0 ? negm : s0, 0, 0, 0);
;         s1 = __builtin_amdgcn_mfma_f32_32x32x16_bf16(a1, qr[d0], d0 == 0 ? negm : s1, 0, 0, 0);
;     }
; }
; __device__ __forceinline__ void attn_unit(const Params& P, unsigned char* lds, int h, int qb) {
;     ...
;         if (act && actn) {
;             const unsigned char* Kn = lds + ((t + 1) & 1) * KBUF + r32 * KROW + hi * 16;
;             SBAR();
; #pragma unroll
;             for (int g = 0; g < 6; ++g) {
;                 const bf16x8 ka = *(const bf16x8*)(Kn + g * 32), kb = *(const bf16x8*)(Kn + 32 * KROW + g * 32);
;                 n0 = __builtin_amdgcn_mfma_f32_32x32x16_bf16(ka, qr[g], g == 0 ? negm : n0, 0, 0, 0);
;                 SBAR();
;                 ATT_GAP((32 * (2 * g)) / 12, (32 * (2 * g + 1)) / 12);
;                 SBAR();
;                 n1 = __builtin_amdgcn_mfma_f32_32x32x16_bf16(kb, qr[g], g == 0 ? negm : n1, 0, 0, 0);
;                 SBAR();
;                 ATT_GAP((32 * (2 * g + 1)) / 12, (32 * (2 * g + 2)) / 12);
;                 SBAR();
;             }
;             if ((t + 1) * 64 + 63 > qw0) attn_mask(n0, n1, (t + 1) * 64, qg, hi);
.LBB0_882:
	s_waitcnt lgkmcnt(3)
	v_mfma_f32_32x32x16_bf16 v[16:31], v[210:213], v[160:163], v[64:79]
	v_exp_f32_e32 v15, v128
	v_exp_f32_e32 v97, v129
	v_exp_f32_e32 v99, v130
	v_cvt_pk_bf16_f32 v2, v15, v97
	s_waitcnt lgkmcnt(2)
	v_mfma_f32_32x32x16_bf16 v[80:95], v[214:217], v[160:163], v[64:79]
	v_exp_f32_e32 v101, v131
	v_exp_f32_e32 v103, v132
	v_cvt_pk_bf16_f32 v3, v99, v101
	v_exp_f32_e32 v105, v133
	ds_read_b128 v[210:213], v208 offset:64
	ds_read_b128 v[214:217], v208 offset:6720
	s_waitcnt lgkmcnt(3)
	v_mfma_f32_32x32x16_bf16 v[16:31], v[218:221], v[144:147], v[16:31]
	v_exp_f32_e32 v107, v134
	v_cvt_pk_bf16_f32 v4, v103, v105
	v_exp_f32_e32 v109, v135
	v_exp_f32_e32 v111, v136
	s_waitcnt lgkmcnt(2)
	v_mfma_f32_32x32x16_bf16 v[80:95], v[222:225], v[144:147], v[80:95]
	v_cvt_pk_bf16_f32 v5, v107, v109
	v_exp_f32_e32 v129, v137
	v_exp_f32_e32 v131, v138
	v_cvt_pk_bf16_f32 v6, v111, v129
	ds_read_b128 v[218:221], v208 offset:96
	ds_read_b128 v[222:225], v208 offset:6752
	s_waitcnt lgkmcnt(3)
	v_mfma_f32_32x32x16_bf16 v[16:31], v[210:213], v[148:151], v[16:31]
	v_exp_f32_e32 v133, v139
	v_exp_f32_e32 v135, v140
	v_cvt_pk_bf16_f32 v7, v131, v133
	v_exp_f32_e32 v137, v141
	s_waitcnt lgkmcnt(2)
	v_mfma_f32_32x32x16_bf16 v[80:95], v[214:217], v[148:151], v[80:95]
	v_exp_f32_e32 v139, v142
	v_cvt_pk_bf16_f32 v8, v135, v137
	v_exp_f32_e32 v141, v143
	v_exp_f32_e32 v14, v112
	ds_read_b128 v[210:213], v208 offset:128
	ds_read_b128 v[214:217], v208 offset:6784
	s_waitcnt lgkmcnt(3)
	v_mfma_f32_32x32x16_bf16 v[16:31], v[218:221], v[152:155], v[16:31]
	v_cvt_pk_bf16_f32 v9, v139, v141
	v_exp_f32_e32 v96, v113
	v_exp_f32_e32 v98, v114
	v_cvt_pk_bf16_f32 v10, v14, v96
	s_waitcnt lgkmcnt(2)
	v_mfma_f32_32x32x16_bf16 v[80:95], v[222:225], v[152:155], v[80:95]
	v_exp_f32_e32 v100, v115
	v_exp_f32_e32 v102, v116
	v_cvt_pk_bf16_f32 v11, v98, v100
	v_exp_f32_e32 v104, v117
	ds_read_b128 v[218:221], v208 offset:160
	ds_read_b128 v[222:225], v208 offset:6816
	s_waitcnt lgkmcnt(3)
	v_mfma_f32_32x32x16_bf16 v[16:31], v[210:213], v[156:159], v[16:31]
	v_exp_f32_e32 v106, v118
	v_cvt_pk_bf16_f32 v12, v102, v104
	v_exp_f32_e32 v108, v119
	v_exp_f32_e32 v110, v120
	s_waitcnt lgkmcnt(2)
	v_mfma_f32_32x32x16_bf16 v[80:95], v[214:217], v[156:159], v[80:95]
	v_cvt_pk_bf16_f32 v13, v106, v108
	v_exp_f32_e32 v128, v121
	v_exp_f32_e32 v130, v122
	v_cvt_pk_bf16_f32 v180, v110, v128
	s_waitcnt lgkmcnt(1)
	v_mfma_f32_32x32x16_bf16 v[16:31], v[218:221], v[164:167], v[16:31]
	v_exp_f32_e32 v132, v123
	v_exp_f32_e32 v134, v124
	v_cvt_pk_bf16_f32 v181, v130, v132
	v_exp_f32_e32 v136, v125
	s_waitcnt lgkmcnt(0)
	v_mfma_f32_32x32x16_bf16 v[80:95], v[222:225], v[164:167], v[80:95]
	v_exp_f32_e32 v138, v126
	v_cvt_pk_bf16_f32 v182, v134, v136
	v_exp_f32_e32 v140, v127
	s_cmp_le_i32 s20, s15
	v_cvt_pk_bf16_f32 v183, v138, v140
	s_cbranch_scc1 .LBB0_884
	s_nop 3
	v_add_u32_e32 v112, s20, v249
	v_subrev_u32_e32 v114, 31, v112
	v_subrev_u32_e32 v113, 63, v112
	v_cmp_le_i32_e32 vcc, v114, v198
	s_nop 1
	v_cndmask_b32_e32 v80, v244, v80, vcc
	v_cmp_lt_i32_e32 vcc, v113, v198
	s_nop 1
	v_cndmask_b32_e32 v17, v244, v17, vcc
	v_cmp_le_i32_e32 vcc, v113, v198
	v_subrev_u32_e32 v113, 30, v112
	s_nop 0
	v_cndmask_b32_e32 v16, v244, v16, vcc
	v_cmp_le_i32_e32 vcc, v113, v198
	v_subrev_u32_e32 v113, 61, v112
	s_nop 0
	v_cndmask_b32_e32 v81, v244, v81, vcc
	v_cmp_le_i32_e32 vcc, v113, v198
	v_subrev_u32_e32 v113, 29, v112
	s_nop 0
	v_cndmask_b32_e32 v18, v244, v18, vcc
	v_cmp_le_i32_e32 vcc, v113, v198
	v_subrev_u32_e32 v113, 60, v112
	s_nop 0
	v_cndmask_b32_e32 v82, v244, v82, vcc
	v_cmp_le_i32_e32 vcc, v113, v198
	v_subrev_u32_e32 v113, 28, v112
	s_nop 0
	v_cndmask_b32_e32 v19, v244, v19, vcc
	v_cmp_le_i32_e32 vcc, v113, v198
	v_subrev_u32_e32 v113, 55, v112
	s_nop 0
	v_cndmask_b32_e32 v83, v244, v83, vcc
	v_cmp_le_i32_e32 vcc, v113, v198
	v_subrev_u32_e32 v113, 23, v112
	s_nop 0
	v_cndmask_b32_e32 v20, v244, v20, vcc
	v_cmp_le_i32_e32 vcc, v113, v198
	v_subrev_u32_e32 v113, 54, v112
	s_nop 0
	v_cndmask_b32_e32 v84, v244, v84, vcc
	v_cmp_le_i32_e32 vcc, v113, v198
	v_subrev_u32_e32 v113, 22, v112
	s_nop 0
	v_cndmask_b32_e32 v21, v244, v21, vcc
	v_cmp_le_i32_e32 vcc, v113, v198
	v_subrev_u32_e32 v113, 53, v112
	s_nop 0
	v_cndmask_b32_e32 v85, v244, v85, vcc
	v_cmp_le_i32_e32 vcc, v113, v198
	v_subrev_u32_e32 v113, 21, v112
	s_nop 0
	v_cndmask_b32_e32 v22, v244, v22, vcc
	v_cmp_le_i32_e32 vcc, v113, v198
	v_subrev_u32_e32 v113, 52, v112
	s_nop 0
	v_cndmask_b32_e32 v86, v244, v86, vcc
	v_cmp_le_i32_e32 vcc, v113, v198
	v_subrev_u32_e32 v113, 20, v112
	s_nop 0
	v_cndmask_b32_e32 v23, v244, v23, vcc
	v_cmp_le_i32_e32 vcc, v113, v198
	v_subrev_u32_e32 v113, 47, v112
	s_nop 0
	v_cndmask_b32_e32 v87, v244, v87, vcc
	v_cmp_le_i32_e32 vcc, v113, v198
	v_add_u32_e32 v113, -15, v112
	s_nop 0
	v_cndmask_b32_e32 v24, v244, v24, vcc
	v_cmp_le_i32_e32 vcc, v113, v198
	v_subrev_u32_e32 v113, 46, v112
	s_nop 0
	v_cndmask_b32_e32 v88, v244, v88, vcc
	v_cmp_le_i32_e32 vcc, v113, v198
	v_add_u32_e32 v113, -14, v112
	s_nop 0
	v_cndmask_b32_e32 v25, v244, v25, vcc
	v_cmp_le_i32_e32 vcc, v113, v198
	v_subrev_u32_e32 v113, 45, v112
	s_nop 0
	v_cndmask_b32_e32 v89, v244, v89, vcc
	v_cmp_le_i32_e32 vcc, v113, v198
	v_add_u32_e32 v113, -13, v112
	s_nop 0
	v_cndmask_b32_e32 v26, v244, v26, vcc
	v_cmp_le_i32_e32 vcc, v113, v198
	v_subrev_u32_e32 v113, 44, v112
	s_nop 0
	v_cndmask_b32_e32 v90, v244, v90, vcc
	v_cmp_le_i32_e32 vcc, v113, v198
	v_add_u32_e32 v113, -12, v112
	s_nop 0
	v_cndmask_b32_e32 v27, v244, v27, vcc
	v_cmp_le_i32_e32 vcc, v113, v198
	v_subrev_u32_e32 v113, 39, v112
	s_nop 0
	v_cndmask_b32_e32 v91, v244, v91, vcc
	v_cmp_le_i32_e32 vcc, v113, v198
	v_add_u32_e32 v113, -7, v112
	s_nop 0
	v_cndmask_b32_e32 v28, v244, v28, vcc
	v_cmp_le_i32_e32 vcc, v113, v198
	v_subrev_u32_e32 v113, 38, v112
	s_nop 0
	v_cndmask_b32_e32 v92, v244, v92, vcc
	v_cmp_le_i32_e32 vcc, v113, v198
	v_add_u32_e32 v113, -6, v112
	s_nop 0
	v_cndmask_b32_e32 v29, v244, v29, vcc
	v_cmp_le_i32_e32 vcc, v113, v198
	v_subrev_u32_e32 v113, 37, v112
	s_nop 0
	v_cndmask_b32_e32 v93, v244, v93, vcc
	v_cmp_le_i32_e32 vcc, v113, v198
	v_add_u32_e32 v113, -5, v112
	s_nop 0
	v_cndmask_b32_e32 v30, v244, v30, vcc
	v_cmp_le_i32_e32 vcc, v113, v198
	v_subrev_u32_e32 v113, 36, v112
	v_add_u32_e32 v112, -4, v112
	v_cndmask_b32_e32 v94, v244, v94, vcc
	v_cmp_le_i32_e32 vcc, v113, v198
	s_nop 1
	v_cndmask_b32_e32 v31, v244, v31, vcc
	v_cmp_le_i32_e32 vcc, v112, v198
	s_nop 1
	v_cndmask_b32_e32 v95, v244, v95, vcc

; #define SBAR() __builtin_amdgcn_sched_barrier(0)
; __device__ __forceinline__ void attn_unit(const Params& P, unsigned char* lds, int h, int qb) {
;     ...
;         if (act && actn) {
;             const unsigned char* Kn = lds + ((t + 1) & 1) * KBUF + r32 * KROW + hi * 16;
;             SBAR();
; #pragma unroll
;             for (int g = 0; g < 6; ++g) {
;                 const bf16x8 ka = *(const bf16x8*)(Kn + g * 32), kb = *(const bf16x8*)(Kn + 32 * KROW + g * 32);
.Lattn_mx:
	s_cmp_ge_i32 s21, s18
	s_cbranch_scc1 .Lattn_nopf
	s_add_i32 s10, s21, 1
	s_bitcmp1_b32 s10, 0
	s_cselect_b32 s10, 0x3400, 0
	v_add_u32_e32 v208, s10, v248
	ds_read_b128 v[210:213], v208
	ds_read_b128 v[214:217], v208 offset:6656
	ds_read_b128 v[218:221], v208 offset:32
	ds_read_b128 v[222:225], v208 offset:6688
